# accumulator zeroing before the K-loops with v_mov_b64 (two registers per instruction)
# speedup vs baseline: 1.0098x; 1.0031x over previous
.LBB0_292:
	s_add_u32 s19, s40, 0x100
	s_addc_u32 s54, s41, 0
	s_add_u32 s55, s38, 0x100
	v_mov_b32_e32 v2, 0
	s_addc_u32 s56, s39, 0
	s_mov_b32 s57, -2
	v_mov_b32_e32 v3, v2
	v_mov_b32_e32 v4, v2
	v_mov_b32_e32 v5, v2
	v_mov_b32_e32 v6, v2
	v_mov_b32_e32 v7, v2
	v_mov_b32_e32 v8, v2
	v_mov_b32_e32 v9, v2
	s_waitcnt vmcnt(0)
	v_mov_b64_e32 v[10:11], 0
	v_mov_b64_e32 v[12:13], 0
	v_mov_b64_e32 v[14:15], 0
	v_mov_b64_e32 v[16:17], 0
	v_mov_b64_e32 v[18:19], 0
	v_mov_b64_e32 v[20:21], 0
	v_mov_b64_e32 v[22:23], 0
	v_mov_b64_e32 v[24:25], 0
	v_mov_b64_e32 v[26:27], 0
	v_mov_b64_e32 v[28:29], 0
	v_mov_b64_e32 v[30:31], 0
	v_mov_b64_e32 v[32:33], 0
	v_mov_b64_e32 v[34:35], 0
	v_mov_b64_e32 v[36:37], 0
	v_mov_b64_e32 v[38:39], 0
	v_mov_b64_e32 v[40:41], 0
	v_mov_b64_e32 v[50:51], 0
	v_mov_b64_e32 v[52:53], 0
	v_mov_b64_e32 v[54:55], 0
	v_mov_b64_e32 v[56:57], 0
	v_mov_b64_e32 v[58:59], 0
	v_mov_b64_e32 v[60:61], 0
	v_mov_b64_e32 v[62:63], 0
	v_mov_b64_e32 v[64:65], 0
	v_mov_b64_e32 v[74:75], 0
	v_mov_b64_e32 v[76:77], 0
	v_mov_b64_e32 v[78:79], 0
	v_mov_b64_e32 v[80:81], 0
	v_mov_b64_e32 v[82:83], 0
	v_mov_b64_e32 v[84:85], 0
	v_mov_b64_e32 v[94:95], 0
	v_mov_b64_e32 v[96:97], 0
	v_mov_b64_e32 v[98:99], 0
	v_mov_b64_e32 v[100:101], 0
	v_mov_b64_e32 v[102:103], 0
	v_mov_b64_e32 v[104:105], 0
	v_mov_b64_e32 v[114:115], 0
	v_mov_b64_e32 v[116:117], 0
	v_mov_b64_e32 v[118:119], 0
	v_mov_b64_e32 v[120:121], 0
	v_mov_b64_e32 v[122:123], 0
	v_mov_b64_e32 v[124:125], 0
	v_mov_b64_e32 v[126:127], 0
	v_mov_b64_e32 v[128:129], 0
	v_mov_b64_e32 v[138:139], 0
	v_mov_b64_e32 v[140:141], 0
	v_mov_b64_e32 v[142:143], 0
	v_mov_b64_e32 v[144:145], 0
	v_mov_b64_e32 v[146:147], 0
	v_mov_b64_e32 v[148:149], 0
	v_mov_b64_e32 v[150:151], 0
	v_mov_b64_e32 v[152:153], 0
	v_mov_b64_e32 v[162:163], 0
	v_mov_b64_e32 v[164:165], 0
	v_mov_b64_e32 v[166:167], 0
	v_mov_b64_e32 v[168:169], 0
	v_mov_b64_e32 v[170:171], 0
	v_mov_b64_e32 v[172:173], 0
	v_mov_b64_e32 v[174:175], 0
	v_mov_b64_e32 v[176:177], 0

.LBB0_1012:
	s_add_u32 s28, s44, 0x100
	s_addc_u32 s29, s45, 0
	s_add_u32 s76, s10, 0x100
	v_mov_b32_e32 v2, 0
	s_addc_u32 s77, s11, 0
	s_mov_b32 s10, 0
	v_mov_b32_e32 v3, v2
	v_mov_b32_e32 v4, v2
	v_mov_b32_e32 v5, v2
	v_mov_b32_e32 v6, v2
	v_mov_b32_e32 v7, v2
	v_mov_b32_e32 v8, v2
	v_mov_b32_e32 v9, v2
	v_mov_b32_e32 v14, v2
	v_mov_b32_e32 v15, v2
	v_mov_b32_e32 v16, v2
	v_mov_b32_e32 v17, v2
	s_waitcnt vmcnt(0)
	v_mov_b64_e32 v[10:11], 0
	v_mov_b64_e32 v[12:13], 0
	v_mov_b64_e32 v[18:19], 0
	v_mov_b64_e32 v[20:21], 0
	v_mov_b64_e32 v[22:23], 0
	v_mov_b64_e32 v[24:25], 0
	v_mov_b64_e32 v[26:27], 0
	v_mov_b64_e32 v[28:29], 0
	v_mov_b64_e32 v[30:31], 0
	v_mov_b64_e32 v[32:33], 0
	v_mov_b64_e32 v[34:35], 0
	v_mov_b64_e32 v[36:37], 0
	v_mov_b64_e32 v[38:39], 0
	v_mov_b64_e32 v[40:41], 0
	v_mov_b64_e32 v[42:43], 0
	v_mov_b64_e32 v[44:45], 0
	v_mov_b64_e32 v[46:47], 0
	v_mov_b64_e32 v[48:49], 0
	v_mov_b64_e32 v[50:51], 0
	v_mov_b64_e32 v[52:53], 0
	v_mov_b64_e32 v[54:55], 0
	v_mov_b64_e32 v[56:57], 0
	v_mov_b64_e32 v[58:59], 0
	v_mov_b64_e32 v[60:61], 0
	v_mov_b64_e32 v[62:63], 0
	v_mov_b64_e32 v[64:65], 0
	v_mov_b64_e32 v[66:67], 0
	v_mov_b64_e32 v[68:69], 0
	v_mov_b64_e32 v[70:71], 0
	v_mov_b64_e32 v[72:73], 0
	v_mov_b64_e32 v[74:75], 0
	v_mov_b64_e32 v[76:77], 0
	v_mov_b64_e32 v[78:79], 0
	v_mov_b64_e32 v[80:81], 0
	v_mov_b64_e32 v[82:83], 0
	v_mov_b64_e32 v[84:85], 0
	v_mov_b64_e32 v[86:87], 0
	v_mov_b64_e32 v[88:89], 0
	v_mov_b64_e32 v[90:91], 0
	v_mov_b64_e32 v[92:93], 0
	v_mov_b64_e32 v[94:95], 0
	v_mov_b64_e32 v[96:97], 0
	v_mov_b64_e32 v[98:99], 0
	v_mov_b64_e32 v[100:101], 0
	v_mov_b64_e32 v[102:103], 0
	v_mov_b64_e32 v[104:105], 0
	v_mov_b64_e32 v[106:107], 0
	v_mov_b64_e32 v[108:109], 0
	v_mov_b64_e32 v[110:111], 0
	v_mov_b64_e32 v[112:113], 0
	v_mov_b64_e32 v[114:115], 0
	v_mov_b64_e32 v[116:117], 0
	v_mov_b64_e32 v[118:119], 0
	v_mov_b64_e32 v[120:121], 0
	v_mov_b64_e32 v[122:123], 0
	v_mov_b64_e32 v[124:125], 0
	v_mov_b64_e32 v[126:127], 0
	v_mov_b64_e32 v[128:129], 0

.LBB0_1025:
	s_mov_b32 s10, 0
	v_mov_b32_e32 v2, 0
	v_mov_b32_e32 v3, 0
	v_mov_b32_e32 v4, 0
	v_mov_b32_e32 v5, 0
	v_mov_b32_e32 v6, 0
	v_mov_b32_e32 v7, 0
	v_mov_b32_e32 v8, 0
	v_mov_b32_e32 v9, 0
	s_waitcnt vmcnt(0)
	v_mov_b64_e32 v[10:11], 0
	v_mov_b64_e32 v[12:13], 0
	v_mov_b64_e32 v[14:15], 0
	v_mov_b64_e32 v[16:17], 0
	v_mov_b64_e32 v[18:19], 0
	v_mov_b64_e32 v[20:21], 0
	v_mov_b64_e32 v[22:23], 0
	v_mov_b64_e32 v[24:25], 0
	v_mov_b64_e32 v[26:27], 0
	v_mov_b64_e32 v[28:29], 0
	v_mov_b64_e32 v[30:31], 0
	v_mov_b64_e32 v[32:33], 0
	v_mov_b64_e32 v[34:35], 0
	v_mov_b64_e32 v[36:37], 0
	v_mov_b64_e32 v[38:39], 0
	v_mov_b64_e32 v[40:41], 0
	v_mov_b64_e32 v[42:43], 0
	v_mov_b64_e32 v[44:45], 0
	v_mov_b64_e32 v[46:47], 0
	v_mov_b64_e32 v[48:49], 0
	v_mov_b64_e32 v[50:51], 0
	v_mov_b64_e32 v[52:53], 0
	v_mov_b64_e32 v[54:55], 0
	v_mov_b64_e32 v[56:57], 0
	v_mov_b64_e32 v[58:59], 0
	v_mov_b64_e32 v[60:61], 0
	v_mov_b64_e32 v[62:63], 0
	v_mov_b64_e32 v[64:65], 0
	v_mov_b64_e32 v[66:67], 0
	v_mov_b64_e32 v[68:69], 0
	v_mov_b64_e32 v[70:71], 0
	v_mov_b64_e32 v[72:73], 0
	v_mov_b64_e32 v[74:75], 0
	v_mov_b64_e32 v[76:77], 0
	v_mov_b64_e32 v[78:79], 0
	v_mov_b64_e32 v[80:81], 0
	v_mov_b64_e32 v[82:83], 0
	v_mov_b64_e32 v[84:85], 0
	v_mov_b64_e32 v[86:87], 0
	v_mov_b64_e32 v[88:89], 0
	v_mov_b64_e32 v[90:91], 0
	v_mov_b64_e32 v[92:93], 0
	v_mov_b64_e32 v[94:95], 0
	v_mov_b64_e32 v[96:97], 0
	v_mov_b64_e32 v[98:99], 0
	v_mov_b64_e32 v[100:101], 0
	v_mov_b64_e32 v[102:103], 0
	v_mov_b64_e32 v[104:105], 0
	v_mov_b64_e32 v[106:107], 0
	v_mov_b64_e32 v[108:109], 0
	v_mov_b64_e32 v[110:111], 0
	v_mov_b64_e32 v[112:113], 0
	v_mov_b64_e32 v[114:115], 0
	v_mov_b64_e32 v[116:117], 0
	v_mov_b64_e32 v[118:119], 0
	v_mov_b64_e32 v[120:121], 0
	v_mov_b64_e32 v[122:123], 0
	v_mov_b64_e32 v[124:125], 0
	v_mov_b64_e32 v[126:127], 0
	v_mov_b64_e32 v[128:129], 0

.LBB0_1213:
	s_add_u32 s23, s48, 0x100
	s_addc_u32 s62, s49, 0
	s_add_u32 s63, s46, 0x100
	v_mov_b32_e32 v2, 0
	s_addc_u32 s64, s47, 0
	s_mov_b32 s65, -2
	v_mov_b32_e32 v3, 0
	v_mov_b64_e32 v[4:5], 0
	v_mov_b64_e32 v[6:7], 0
	v_mov_b64_e32 v[8:9], 0
	v_mov_b64_e32 v[10:11], 0
	v_mov_b64_e32 v[12:13], 0
	v_mov_b64_e32 v[14:15], 0
	v_mov_b64_e32 v[16:17], 0
	v_mov_b64_e32 v[18:19], 0
	v_mov_b64_e32 v[20:21], 0
	v_mov_b64_e32 v[22:23], 0
	v_mov_b64_e32 v[24:25], 0
	v_mov_b64_e32 v[26:27], 0
	v_mov_b64_e32 v[28:29], 0
	v_mov_b64_e32 v[30:31], 0
	v_mov_b64_e32 v[32:33], 0
	v_mov_b64_e32 v[34:35], 0
	v_mov_b64_e32 v[36:37], 0
	v_mov_b64_e32 v[38:39], 0
	v_mov_b64_e32 v[40:41], 0
	v_mov_b64_e32 v[42:43], 0
	v_mov_b64_e32 v[44:45], 0
	v_mov_b64_e32 v[46:47], 0
	v_mov_b64_e32 v[48:49], 0
	v_mov_b64_e32 v[50:51], 0
	v_mov_b64_e32 v[52:53], 0
	v_mov_b64_e32 v[54:55], 0
	v_mov_b64_e32 v[56:57], 0
	v_mov_b64_e32 v[58:59], 0
	v_mov_b64_e32 v[60:61], 0
	v_mov_b64_e32 v[62:63], 0
	v_mov_b64_e32 v[64:65], 0
	v_mov_b64_e32 v[66:67], 0
	v_mov_b64_e32 v[68:69], 0
	v_mov_b64_e32 v[70:71], 0
	v_mov_b64_e32 v[72:73], 0
	v_mov_b64_e32 v[74:75], 0
	v_mov_b64_e32 v[76:77], 0
	v_mov_b64_e32 v[78:79], 0
	v_mov_b64_e32 v[80:81], 0
	v_mov_b64_e32 v[82:83], 0
	v_mov_b64_e32 v[84:85], 0
	v_mov_b64_e32 v[86:87], 0
	v_mov_b64_e32 v[88:89], 0
	v_mov_b64_e32 v[90:91], 0
	v_mov_b64_e32 v[92:93], 0
	v_mov_b64_e32 v[94:95], 0
	v_mov_b64_e32 v[96:97], 0
	v_mov_b64_e32 v[98:99], 0
	v_mov_b64_e32 v[100:101], 0
	v_mov_b64_e32 v[102:103], 0
	v_mov_b64_e32 v[104:105], 0
	v_mov_b64_e32 v[106:107], 0
	v_mov_b64_e32 v[108:109], 0
	v_mov_b64_e32 v[110:111], 0
	v_mov_b64_e32 v[112:113], 0
	v_mov_b64_e32 v[114:115], 0
	v_mov_b64_e32 v[116:117], 0
	v_mov_b64_e32 v[118:119], 0
	v_mov_b64_e32 v[120:121], 0
	v_mov_b64_e32 v[122:123], 0
	v_mov_b64_e32 v[124:125], 0
	v_mov_b64_e32 v[126:127], 0
	v_mov_b64_e32 v[128:129], 0
